# GEMM K-loop heads aligned to 64 bytes (code placement)
# baseline (speedup 1.0000x reference)
; template <class Epi, class Sched, bool ALIGN_EPI = false, bool SP2 = false>
; __device__ __forceinline__ void gemm_phase(PG8_LAS unsigned char* lds, const Gemm g, const Sched& S, const Epi& E) {
;     ...
;         const bool has_next = S.next(ui + 1, nxt);
;         const char* nA = has_next ? (const char*)g.A + (size_t)nxt.pm * tstep : cA; const char* nB = has_next ? (const char*)g.Bt + (size_t)nxt.pn * tstep : cB;
;         for (int t = 0; t < nt; t += 2) {
;     ...
; #pragma unroll
;         for (int a = 0; a < 2; ++a)
; #pragma unroll
;             for (int b = 0; b < 2; ++b)
; #pragma unroll
;                 for (int m = 0; m < 4; ++m)
; #pragma unroll
;                     for (int n = 0; n < 2; ++n) acc[a][b][m][n] = (f32x4){0.f, 0.f, 0.f, 0.f};
;         cur = nxt; cA = nA; cB = nB; ++ui;
.LBB0_693:
	s_ashr_i32 s21, s20, 31
	s_lshl_b64 s[22:23], s[20:21], 19
	s_add_u32 s22, s12, s22
	s_addc_u32 s23, s13, s23
	s_and_b64 s[24:25], s[0:1], exec
	s_cselect_b32 s21, s23, s29
	s_cselect_b32 vcc_lo, s22, s28
	s_ashr_i32 s19, s18, 31
	s_lshl_b64 s[24:25], s[18:19], 19
	s_add_u32 s24, s10, s24
	s_addc_u32 s25, s11, s25
	s_and_b64 s[34:35], s[0:1], exec
	s_cselect_b32 s19, s25, s31
	s_cselect_b32 vcc_hi, s24, s30
	s_add_u32 s28, s28, 0x40080
	s_addc_u32 s29, s29, 0
	s_add_u32 s54, s30, 0x100
	v_mov_b32_e32 v4, 0
	s_addc_u32 s55, s31, 0
	s_mov_b32 s52, -2
	v_mov_b32_e32 v5, v4
	v_mov_b32_e32 v6, v4
	v_mov_b32_e32 v7, v4
	v_mov_b32_e32 v8, v4
	v_mov_b32_e32 v9, v4
	v_mov_b32_e32 v10, v4
	v_mov_b32_e32 v11, v4
	v_mov_b32_e32 v16, v4
	v_mov_b32_e32 v17, v4
	v_mov_b32_e32 v18, v4
	v_mov_b32_e32 v19, v4
	v_mov_b32_e32 v24, v4
	v_mov_b32_e32 v25, v4
	v_mov_b32_e32 v26, v4
	v_mov_b32_e32 v27, v4
	v_mov_b32_e32 v32, v4
	v_mov_b32_e32 v33, v4
	v_mov_b32_e32 v34, v4
	v_mov_b32_e32 v35, v4
	v_mov_b32_e32 v40, v4
	v_mov_b32_e32 v41, v4
	v_mov_b32_e32 v42, v4
	v_mov_b32_e32 v43, v4
	v_mov_b32_e32 v48, v4
	v_mov_b32_e32 v49, v4
	v_mov_b32_e32 v50, v4
	v_mov_b32_e32 v51, v4
	v_mov_b32_e32 v56, v4
	v_mov_b32_e32 v57, v4
	v_mov_b32_e32 v58, v4
	v_mov_b32_e32 v59, v4
	v_mov_b32_e32 v12, v4
	v_mov_b32_e32 v13, v4
	v_mov_b32_e32 v14, v4
	v_mov_b32_e32 v15, v4
	v_mov_b32_e32 v20, v4
	v_mov_b32_e32 v21, v4
	v_mov_b32_e32 v22, v4
	v_mov_b32_e32 v23, v4
	v_mov_b32_e32 v28, v4
	v_mov_b32_e32 v29, v4
	v_mov_b32_e32 v30, v4
	v_mov_b32_e32 v31, v4
	v_mov_b32_e32 v36, v4
	v_mov_b32_e32 v37, v4
	v_mov_b32_e32 v38, v4
	v_mov_b32_e32 v39, v4
	v_mov_b32_e32 v44, v4
	v_mov_b32_e32 v45, v4
	v_mov_b32_e32 v46, v4
	v_mov_b32_e32 v47, v4
	v_mov_b32_e32 v52, v4
	v_mov_b32_e32 v53, v4
	v_mov_b32_e32 v54, v4
	v_mov_b32_e32 v55, v4
	v_mov_b32_e32 v60, v4
	v_mov_b32_e32 v61, v4
	v_mov_b32_e32 v62, v4
	v_mov_b32_e32 v63, v4
	v_mov_b32_e32 v64, v4
	v_mov_b32_e32 v65, v4
	v_mov_b32_e32 v66, v4
	v_mov_b32_e32 v67, v4
	v_mov_b32_e32 v68, v4
	v_mov_b32_e32 v69, v4
	v_mov_b32_e32 v70, v4
	v_mov_b32_e32 v71, v4
	v_mov_b32_e32 v72, v4
	v_mov_b32_e32 v73, v4
	v_mov_b32_e32 v74, v4
	v_mov_b32_e32 v75, v4
	v_mov_b32_e32 v80, v4
	v_mov_b32_e32 v81, v4
	v_mov_b32_e32 v82, v4
	v_mov_b32_e32 v83, v4
	v_mov_b32_e32 v88, v4
	v_mov_b32_e32 v89, v4
	v_mov_b32_e32 v90, v4
	v_mov_b32_e32 v91, v4
	v_mov_b32_e32 v96, v4
	v_mov_b32_e32 v97, v4
	v_mov_b32_e32 v98, v4
	v_mov_b32_e32 v99, v4
	v_mov_b32_e32 v104, v4
	v_mov_b32_e32 v105, v4
	v_mov_b32_e32 v106, v4
	v_mov_b32_e32 v107, v4
	v_mov_b32_e32 v112, v4
	v_mov_b32_e32 v113, v4
	v_mov_b32_e32 v114, v4
	v_mov_b32_e32 v115, v4
	v_mov_b32_e32 v120, v4
	v_mov_b32_e32 v121, v4
	v_mov_b32_e32 v122, v4
	v_mov_b32_e32 v123, v4
	v_mov_b32_e32 v76, v4
	v_mov_b32_e32 v77, v4
	v_mov_b32_e32 v78, v4
	v_mov_b32_e32 v79, v4
	v_mov_b32_e32 v84, v4
	v_mov_b32_e32 v85, v4
	v_mov_b32_e32 v86, v4
	v_mov_b32_e32 v87, v4
	v_mov_b32_e32 v92, v4
	v_mov_b32_e32 v93, v4
	v_mov_b32_e32 v94, v4
	v_mov_b32_e32 v95, v4
	v_mov_b32_e32 v100, v4
	v_mov_b32_e32 v101, v4
	v_mov_b32_e32 v102, v4
	v_mov_b32_e32 v103, v4
	v_mov_b32_e32 v108, v4
	v_mov_b32_e32 v109, v4
	v_mov_b32_e32 v110, v4
	v_mov_b32_e32 v111, v4
	v_mov_b32_e32 v116, v4
	v_mov_b32_e32 v117, v4
	v_mov_b32_e32 v118, v4
	v_mov_b32_e32 v119, v4
	v_mov_b32_e32 v124, v4
	v_mov_b32_e32 v125, v4
	v_mov_b32_e32 v126, v4
	v_mov_b32_e32 v127, v4
	v_mov_b32_e32 v128, v4
	v_mov_b32_e32 v129, v4
	v_mov_b32_e32 v130, v4
	v_mov_b32_e32 v131, v4
	.p2align 6

; template <class Epi, class Sched, bool ALIGN_EPI = false, bool SP2 = false>
; __device__ __forceinline__ void gemm_phase(PG8_LAS unsigned char* lds, const Gemm g, const Sched& S, const Epi& E) {
;     ...
;         for (int t = 0; t < nt; t += 2) {
;             const bool last = (t == nt - 2);
;             const char* a1 = cA + (size_t)(t + 1) * kstep;
;             const char* a2 = last ? nA : cA + (size_t)(t + 2) * kstep; const char* b2 = last ? nB : cB + (size_t)(t + 2) * kstep;
;             const char* a3 = a2 + kstep; const char* b3 = b2 + kstep;
.LBB0_719:
	s_mov_b32 s20, 0
	s_mov_b64 s[18:19], 0x100
	v_mov_b64_e32 v[108:109], v[106:107]
	v_mov_b64_e32 v[110:111], v[104:105]
	.p2align 6

; template <class Epi, class Sched, bool ALIGN_EPI = false, bool SP2 = false>
; __device__ __forceinline__ void gemm_phase(PG8_LAS unsigned char* lds, const Gemm g, const Sched& S, const Epi& E) {
;     ...
;         const bool has_next = S.next(ui + 1, nxt);
;         const char* nA = has_next ? (const char*)g.A + (size_t)nxt.pm * tstep : cA; const char* nB = has_next ? (const char*)g.Bt + (size_t)nxt.pn * tstep : cB;
;         for (int t = 0; t < nt; t += 2) {
;     ...
; #pragma unroll
;         for (int a = 0; a < 2; ++a)
; #pragma unroll
;             for (int b = 0; b < 2; ++b)
; #pragma unroll
;                 for (int m = 0; m < 4; ++m)
; #pragma unroll
;                     for (int n = 0; n < 2; ++n) acc[a][b][m][n] = (f32x4){0.f, 0.f, 0.f, 0.f};
;         cur = nxt; cA = nA; cB = nB; ++ui;
.LBB0_882:
	s_ashr_i32 s11, s10, 31
	s_lshl_b64 s[12:13], s[10:11], 19
	v_readlane_b32 s14, v253, 58
	v_readlane_b32 s15, v253, 59
	s_add_u32 s12, s14, s12
	s_addc_u32 s13, s15, s13
	s_and_b64 s[14:15], s[0:1], exec
	s_cselect_b32 s11, s13, s17
	s_cselect_b32 s33, s12, s16
	s_ashr_i32 s9, s8, 31
	s_lshl_b64 s[14:15], s[8:9], 19
	v_readlane_b32 s9, v255, 28
	s_add_u32 s14, s9, s14
	v_readlane_b32 s9, v255, 29
	s_addc_u32 s15, s9, s15
	s_and_b64 s[20:21], s[0:1], exec
	s_cselect_b32 s9, s15, s19
	s_cselect_b32 s34, s14, s18
	s_add_u32 s16, s16, 0x40080
	s_addc_u32 s17, s17, 0
	s_add_u32 s35, s18, 0x100
	v_mov_b32_e32 v4, 0
	s_addc_u32 s38, s19, 0
	s_mov_b32 s39, -2
	v_mov_b32_e32 v5, v4
	v_mov_b32_e32 v6, v4
	v_mov_b32_e32 v7, v4
	v_mov_b32_e32 v8, v4
	v_mov_b32_e32 v9, v4
	v_mov_b32_e32 v10, v4
	v_mov_b32_e32 v11, v4
	v_mov_b32_e32 v20, v4
	v_mov_b32_e32 v21, v4
	v_mov_b32_e32 v22, v4
	v_mov_b32_e32 v23, v4
	v_mov_b32_e32 v24, v4
	v_mov_b32_e32 v25, v4
	v_mov_b32_e32 v26, v4
	v_mov_b32_e32 v27, v4
	v_mov_b32_e32 v36, v4
	v_mov_b32_e32 v37, v4
	v_mov_b32_e32 v38, v4
	v_mov_b32_e32 v39, v4
	v_mov_b32_e32 v40, v4
	v_mov_b32_e32 v41, v4
	v_mov_b32_e32 v42, v4
	v_mov_b32_e32 v43, v4
	v_mov_b32_e32 v52, v4
	v_mov_b32_e32 v53, v4
	v_mov_b32_e32 v54, v4
	v_mov_b32_e32 v55, v4
	v_mov_b32_e32 v56, v4
	v_mov_b32_e32 v57, v4
	v_mov_b32_e32 v58, v4
	v_mov_b32_e32 v59, v4
	v_mov_b32_e32 v12, v4
	v_mov_b32_e32 v13, v4
	v_mov_b32_e32 v14, v4
	v_mov_b32_e32 v15, v4
	v_mov_b32_e32 v16, v4
	v_mov_b32_e32 v17, v4
	v_mov_b32_e32 v18, v4
	v_mov_b32_e32 v19, v4
	v_mov_b32_e32 v28, v4
	v_mov_b32_e32 v29, v4
	v_mov_b32_e32 v30, v4
	v_mov_b32_e32 v31, v4
	v_mov_b32_e32 v32, v4
	v_mov_b32_e32 v33, v4
	v_mov_b32_e32 v34, v4
	v_mov_b32_e32 v35, v4
	v_mov_b32_e32 v44, v4
	v_mov_b32_e32 v45, v4
	v_mov_b32_e32 v46, v4
	v_mov_b32_e32 v47, v4
	v_mov_b32_e32 v48, v4
	v_mov_b32_e32 v49, v4
	v_mov_b32_e32 v50, v4
	v_mov_b32_e32 v51, v4
	v_mov_b32_e32 v60, v4
	v_mov_b32_e32 v61, v4
	v_mov_b32_e32 v62, v4
	v_mov_b32_e32 v63, v4
	v_mov_b32_e32 v64, v4
	v_mov_b32_e32 v65, v4
	v_mov_b32_e32 v66, v4
	v_mov_b32_e32 v67, v4
	v_mov_b32_e32 v68, v4
	v_mov_b32_e32 v69, v4
	v_mov_b32_e32 v70, v4
	v_mov_b32_e32 v71, v4
	v_mov_b32_e32 v72, v4
	v_mov_b32_e32 v73, v4
	v_mov_b32_e32 v74, v4
	v_mov_b32_e32 v75, v4
	v_mov_b32_e32 v84, v4
	v_mov_b32_e32 v85, v4
	v_mov_b32_e32 v86, v4
	v_mov_b32_e32 v87, v4
	v_mov_b32_e32 v88, v4
	v_mov_b32_e32 v89, v4
	v_mov_b32_e32 v90, v4
	v_mov_b32_e32 v91, v4
	v_mov_b32_e32 v100, v4
	v_mov_b32_e32 v101, v4
	v_mov_b32_e32 v102, v4
	v_mov_b32_e32 v103, v4
	v_mov_b32_e32 v104, v4
	v_mov_b32_e32 v105, v4
	v_mov_b32_e32 v106, v4
	v_mov_b32_e32 v107, v4
	v_mov_b32_e32 v116, v4
	v_mov_b32_e32 v117, v4
	v_mov_b32_e32 v118, v4
	v_mov_b32_e32 v119, v4
	v_mov_b32_e32 v120, v4
	v_mov_b32_e32 v121, v4
	v_mov_b32_e32 v122, v4
	v_mov_b32_e32 v123, v4
	v_mov_b32_e32 v76, v4
	v_mov_b32_e32 v77, v4
	v_mov_b32_e32 v78, v4
	v_mov_b32_e32 v79, v4
	v_mov_b32_e32 v80, v4
	v_mov_b32_e32 v81, v4
	v_mov_b32_e32 v82, v4
	v_mov_b32_e32 v83, v4
	v_mov_b32_e32 v92, v4
	v_mov_b32_e32 v93, v4
	v_mov_b32_e32 v94, v4
	v_mov_b32_e32 v95, v4
	v_mov_b32_e32 v96, v4
	v_mov_b32_e32 v97, v4
	v_mov_b32_e32 v98, v4
	v_mov_b32_e32 v99, v4
	v_mov_b32_e32 v108, v4
	v_mov_b32_e32 v109, v4
	v_mov_b32_e32 v110, v4
	v_mov_b32_e32 v111, v4
	v_mov_b32_e32 v112, v4
	v_mov_b32_e32 v113, v4
	v_mov_b32_e32 v114, v4
	v_mov_b32_e32 v115, v4
	v_mov_b32_e32 v124, v4
	v_mov_b32_e32 v125, v4
	v_mov_b32_e32 v126, v4
	v_mov_b32_e32 v127, v4
	v_mov_b32_e32 v128, v4
	v_mov_b32_e32 v129, v4
	v_mov_b32_e32 v130, v4
	v_mov_b32_e32 v131, v4
	.p2align 6
